# prologue: write-through (sc0 sc1) stores of the normalized x rows so the chip-wide barrier's L2 write-back finds them clean
# speedup vs baseline: 1.0041x; 1.0041x over previous
.LBB0_271:
	s_or_b64 exec, exec, s[4:5]
	v_div_scale_f32 v32, s[4:5], v31, v31, 1.0
	v_rcp_f32_e32 v33, v32
	s_lshl_b64 s[4:5], s[10:11], 10
	s_add_i32 s12, s12, s13
	s_sub_i32 s14, s14, s13
	v_fma_f32 v34, -v32, v33, 1.0
	v_fmac_f32_e32 v33, v34, v33
	v_div_scale_f32 v34, vcc, 1.0, v31, 1.0
	v_mul_f32_e32 v35, v34, v33
	v_fma_f32 v36, -v32, v35, v34
	v_fmac_f32_e32 v35, v36, v33
	v_fma_f32 v32, -v32, v35, v34
	v_div_fmas_f32 v32, v32, v33, v35
	v_div_fixup_f32 v31, v32, v31, 1.0
	v_mul_f32_e32 v14, v14, v31
	v_mul_f32_e32 v15, v15, v31
	v_bfe_u32 v34, v14, 16, 1
	v_add3_u32 v14, v14, v34, s16
	v_bfe_u32 v34, v15, 16, 1
	v_lshrrev_b32_e32 v14, 16, v14
	v_add3_u32 v15, v15, v34, s16
	v_and_or_b32 v14, v15, s17, v14
	v_mul_f32_e32 v15, v16, v31
	v_mul_f32_e32 v16, v17, v31
	v_bfe_u32 v17, v15, 16, 1
	v_add3_u32 v15, v15, v17, s16
	v_bfe_u32 v17, v16, 16, 1
	v_lshrrev_b32_e32 v15, 16, v15
	v_add3_u32 v16, v16, v17, s16
	v_lshl_add_u64 v[32:33], s[4:5], 1, v[22:23]
	v_and_or_b32 v15, v16, s17, v15
	v_mul_f32_e32 v10, v10, v31
	global_store_dwordx2 v[32:33], v[14:15], off sc0 sc1
	v_mul_f32_e32 v11, v11, v31
	v_bfe_u32 v14, v10, 16, 1
	v_add3_u32 v10, v10, v14, s16
	v_bfe_u32 v14, v11, 16, 1
	v_lshrrev_b32_e32 v10, 16, v10
	v_add3_u32 v11, v11, v14, s16
	v_and_or_b32 v10, v11, s17, v10
	v_mul_f32_e32 v11, v12, v31
	v_mul_f32_e32 v12, v13, v31
	v_bfe_u32 v13, v11, 16, 1
	v_add3_u32 v11, v11, v13, s16
	v_bfe_u32 v13, v12, 16, 1
	v_lshrrev_b32_e32 v11, 16, v11
	v_add3_u32 v12, v12, v13, s16
	v_and_or_b32 v11, v12, s17, v11
	v_mul_f32_e32 v6, v6, v31
	global_store_dwordx2 v[32:33], v[10:11], off offset:512 sc0 sc1
	v_mul_f32_e32 v7, v7, v31
	v_bfe_u32 v10, v6, 16, 1
	v_add3_u32 v6, v6, v10, s16
	v_bfe_u32 v10, v7, 16, 1
	v_lshrrev_b32_e32 v6, 16, v6
	v_add3_u32 v7, v7, v10, s16
	v_and_or_b32 v6, v7, s17, v6
	v_mul_f32_e32 v7, v8, v31
	v_mul_f32_e32 v8, v9, v31
	v_bfe_u32 v9, v7, 16, 1
	v_add3_u32 v7, v7, v9, s16
	v_bfe_u32 v9, v8, 16, 1
	v_lshrrev_b32_e32 v7, 16, v7
	v_add3_u32 v8, v8, v9, s16
	v_and_or_b32 v7, v8, s17, v7
	v_mul_f32_e32 v2, v2, v31
	global_store_dwordx2 v[32:33], v[6:7], off offset:1024 sc0 sc1
	v_mul_f32_e32 v3, v3, v31
	v_bfe_u32 v6, v2, 16, 1
	v_add3_u32 v2, v2, v6, s16
	v_bfe_u32 v6, v3, 16, 1
	v_lshrrev_b32_e32 v2, 16, v2
	v_add3_u32 v3, v3, v6, s16
	v_and_or_b32 v2, v3, s17, v2
	v_mul_f32_e32 v3, v4, v31
	v_mul_f32_e32 v4, v5, v31
	v_bfe_u32 v5, v3, 16, 1
	v_add3_u32 v3, v3, v5, s16
	v_bfe_u32 v5, v4, 16, 1
	v_lshrrev_b32_e32 v3, 16, v3
	v_add3_u32 v4, v4, v5, s16
	v_and_or_b32 v3, v4, s17, v3
	s_cmp_lt_i32 s12, s7
	global_store_dwordx2 v[32:33], v[2:3], off offset:1536 sc0 sc1
	s_cbranch_scc0 .LBB0_274
